# sec 7.11: MLA and window flash loops - counter/exit test/next-tile control moved in front of the loop-back barrier, exit path has its own barrier
# baseline (speedup 1.0000x reference)
; DI void lds_barrier() { asm volatile("s_waitcnt lgkmcnt(0)" ::: "memory"); __builtin_amdgcn_s_barrier(); asm volatile("" ::: "memory"); }
; #define FP_GLOAD(jt) do { const size_t k0_ = (size_t)(jt) * 64; \
;         kreg0 = *(const u32x4*)(Kg + (k0_ + krow0) * kpitch + kc0 * 8); \
;         if (NCH > 512 && tid + 512 < NCH) kreg1 = *(const u32x4*)(Kg + (k0_ + krow1) * kpitch + kc1 * 8); \
;         if (MODE != 1) vreg = *(const u32x4*)(Vg + (k0_ + vkey) * vpitch + vc * 8); } while (0)
; #define FP_LSTORE(buf) do { LAS char* Kd_ = lds + ATT_K_OFF + (buf) * ATT_KSZ; LAS char* Vd_ = lds + ATT_V_OFF + (buf) * ATT_VSZ; \
;         *(LAS u32x4*)(Kd_ + krow0 * KP + kc0 * 16) = kreg0; \
;         if (NCH > 512 && tid + 512 < NCH) *(LAS u32x4*)(Kd_ + krow1 * KP + kc1 * 16) = kreg1; \
;         if (MODE != 1) *(LAS u32x4*)(Vd_ + vkey * VP + vc * 16) = vreg; } while (0)
; template <int DQK, int MODE, class Mask> ...
;     ...
;     for (int j = tile_lo; j < tile_hi; ++j) {
;         const int cur = (j - tile_lo) & 1;
;         if (j + 1 < tile_hi) FP_LSTORE(cur ^ 1);
;         if (j + 2 < tile_hi) FP_GLOAD(j + 2);
;         if (j < wave_tile_hi) {
;     ...
;         lds_barrier();
.LBB0_1056:
	s_add_i32 s43, s43, 64
	v_lshl_add_u64 v[208:209], v[208:209], 0, s[46:47]
	v_lshl_add_u64 v[206:207], v[206:207], 0, s[34:35]
	s_cmp_eq_u32 s41, s44
	v_lshl_add_u64 v[204:205], v[204:205], 0, s[46:47]
	s_cbranch_scc1 .Lbe_mla_exit
	s_mov_b32 s16, s44
	s_and_b32 s17, s16, 1
	s_add_i32 s44, s16, 1
	s_waitcnt lgkmcnt(0)
	s_barrier
	s_cmp_ge_i32 s44, s41
	s_cbranch_scc0 .LBB0_1043
	s_branch .LBB0_1041
.Lbe_mla_exit:
	s_waitcnt lgkmcnt(0)
	s_barrier
	s_branch .LBB0_1027

; DI void lds_barrier() { asm volatile("s_waitcnt lgkmcnt(0)" ::: "memory"); __builtin_amdgcn_s_barrier(); asm volatile("" ::: "memory"); }
; #define FP_GLOAD(jt) do { const size_t k0_ = (size_t)(jt) * 64; \
;         kreg0 = *(const u32x4*)(Kg + (k0_ + krow0) * kpitch + kc0 * 8); \
;         if (NCH > 512 && tid + 512 < NCH) kreg1 = *(const u32x4*)(Kg + (k0_ + krow1) * kpitch + kc1 * 8); \
;         if (MODE != 1) vreg = *(const u32x4*)(Vg + (k0_ + vkey) * vpitch + vc * 8); } while (0)
; #define FP_LSTORE(buf) do { LAS char* Kd_ = lds + ATT_K_OFF + (buf) * ATT_KSZ; LAS char* Vd_ = lds + ATT_V_OFF + (buf) * ATT_VSZ; \
;         *(LAS u32x4*)(Kd_ + krow0 * KP + kc0 * 16) = kreg0; \
;         if (NCH > 512 && tid + 512 < NCH) *(LAS u32x4*)(Kd_ + krow1 * KP + kc1 * 16) = kreg1; \
;         if (MODE != 1) *(LAS u32x4*)(Vd_ + vkey * VP + vc * 16) = vreg; } while (0)
; template <int DQK, int MODE, class Mask> ...
;     ...
;     for (int j = tile_lo; j < tile_hi; ++j) {
;         const int cur = (j - tile_lo) & 1;
;         if (j + 1 < tile_hi) FP_LSTORE(cur ^ 1);
;         if (j + 2 < tile_hi) FP_GLOAD(j + 2);
;         if (j < wave_tile_hi) {
;     ...
;         lds_barrier();
.LBB0_1116:
	s_add_i32 s50, s50, 1
	s_add_i32 s16, s20, s50
	s_add_i32 s16, s16, -9
	v_add_u32_e32 v208, 64, v208
	v_lshl_add_u64 v[214:215], v[214:215], 0, s[48:49]
	s_cmp_ge_u32 s16, s68
	v_lshl_add_u64 v[216:217], v[216:217], 0, s[48:49]
	s_cbranch_scc1 .Lbe_win_exit
	s_waitcnt lgkmcnt(0)
	s_barrier

; #define LAS __attribute__((address_space(3)))
; DI float fexp2(float x) { return __builtin_amdgcn_exp2f(x); }
; DI f32x16 zero16() { return (f32x16){0.f, 0.f, 0.f, 0.f, 0.f, 0.f, 0.f, 0.f, 0.f, 0.f, 0.f, 0.f, 0.f, 0.f, 0.f, 0.f}; }
; template <int DQK, int MODE, class Mask> ...
;     ...
;                     const float dl = need ? mt : 0.f;
;                     const float alpha = href ? fexp2(-dl) : 0.f;
;                     mref += dl; href = href || need;
; #pragma unroll
;                     for (int kb = 0; kb < 2; ++kb)
; #pragma unroll
;                         for (int i = 0; i < 16; ++i) s[kb][i] -= dl;
; #pragma unroll
;                     for (int i = 0; i < 16; ++i) { negm16[i] = -mref; ol[i] *= alpha; }
;                     if (MODE == 0) {
; #pragma unroll
;                         for (int d = 0; d < 2; ++d)
; #pragma unroll
;                             for (int i = 0; i < 16; ++i) o[d][i] *= alpha;
;                     }
;                 }
; DI void nsa_unit(LAS char* lds, int b, int g, int qb, const bf16* Z, const bf16* KC, const bf16* VC, bf16* On, int tid, int lane, int wave) {
;     ...
;     {
;         MaskWin mk{t, qb};
;         float m_run = -1e29f, l_run = 0.f; o[0] = zero16(); o[1] = zero16();
;         const bf16* Kg = Z + m0 * ZP + C_KVN + 4 * 128 + g * 64; const bf16* Vg = Z + m0 * ZP + C_KVN + 5 * 128 + g * 64;
;         const int lo = qb - 8 > 0 ? qb - 8 : 0;
;         flash_pass<64, 0>(lds, Kg, ZP, Vg, ZP, lo, qb + 1, qb + 1, qf, sc, mk, m_run, l_run, o, (LAS float*)nullptr, tid, lane);
;         const float w = g2 / l_run;
; #pragma unroll
;         for (int d = 0; d < 2; ++d)
; #pragma unroll
;             for (int i = 0; i < 16; ++i) o[d][i] = stash[(d * 16 + i) * 64] + w * o[d][i];
.LBB0_1124:
	s_nop 15
	s_nop 7
	s_mov_b64 s[16:17], -1
	v_max3_f32 v0, v82, v83, v84
	v_max3_f32 v212, v66, v67, v68
	s_nop 0
	v_max3_f32 v0, v0, v85, v86
	v_max3_f32 v212, v212, v69, v70
	s_nop 0
	v_max3_f32 v0, v0, v87, v88
	v_max3_f32 v212, v212, v71, v72
	s_nop 0
	v_max3_f32 v0, v0, v89, v90
	v_max3_f32 v212, v212, v73, v74
	s_nop 0
	v_max3_f32 v0, v0, v91, v92
	v_max3_f32 v212, v212, v75, v76
	s_nop 0
	v_max3_f32 v0, v0, v93, v94
	v_max3_f32 v212, v212, v77, v78
	s_nop 0
	v_max3_f32 v0, v0, v95, v96
	v_max3_f32 v212, v212, v79, v80
	s_nop 0
	v_max3_f32 v0, v0, v97, v81
	s_nop 0
	v_max_f32 v0, v0, v212
	s_nop 0
	v_mov_b32_e32 v212, v0
	s_nop 1
	v_permlane32_swap_b32_e32 v0, v212
	v_max_f32_e32 v212, v212, v212
	v_max_f32_e32 v0, v0, v0
	v_max_f32_e32 v0, v0, v212
	v_cmp_lt_f32_e32 vcc, s60, v0
	v_cmp_lt_f32_e64 s[18:19], s61, v0
	s_andn2_b64 s[18:19], s[18:19], s[12:13]
	s_or_b64 s[16:17], vcc, s[18:19]
	s_cbranch_scc0 .LBB0_1115
	v_cndmask_b32_e64 v50, 0, v0, s[16:17]
	v_exp_f32_e64 v0, -v50
	v_add_f32_e32 v210, v210, v50
	s_or_b64 s[16:17], s[12:13], s[16:17]
	v_sub_f32_e32 v82, v82, v50
	v_sub_f32_e32 v83, v83, v50
	v_sub_f32_e32 v84, v84, v50
	v_cndmask_b32_e64 v0, 0, v0, s[12:13]
	v_sub_f32_e32 v85, v85, v50
	v_sub_f32_e32 v86, v86, v50
	v_sub_f32_e32 v87, v87, v50
	v_sub_f32_e32 v88, v88, v50
	v_sub_f32_e32 v89, v89, v50
	v_sub_f32_e32 v90, v90, v50
	v_sub_f32_e32 v91, v91, v50
	v_sub_f32_e32 v92, v92, v50
	v_sub_f32_e32 v93, v93, v50
	v_sub_f32_e32 v94, v94, v50
	v_sub_f32_e32 v95, v95, v50
	v_sub_f32_e32 v96, v96, v50
	v_sub_f32_e32 v97, v97, v50
	v_sub_f32_e32 v66, v66, v50
	v_sub_f32_e32 v67, v67, v50
	v_sub_f32_e32 v68, v68, v50
	v_sub_f32_e32 v69, v69, v50
	v_sub_f32_e32 v70, v70, v50
	v_sub_f32_e32 v71, v71, v50
	v_sub_f32_e32 v72, v72, v50
	v_sub_f32_e32 v73, v73, v50
	v_sub_f32_e32 v74, v74, v50
	v_sub_f32_e32 v75, v75, v50
	v_sub_f32_e32 v76, v76, v50
	v_sub_f32_e32 v77, v77, v50
	v_sub_f32_e32 v78, v78, v50
	v_sub_f32_e32 v79, v79, v50
	v_sub_f32_e32 v80, v80, v50
	v_sub_f32_e32 v81, v81, v50
	v_xor_b32_e32 v50, 0x80000000, v210
	s_andn2_b64 s[12:13], s[12:13], exec
	s_and_b64 s[16:17], s[16:17], exec
	v_pk_mul_f32 v[48:49], v[48:49], v[0:1] op_sel_hi:[1,0]
	v_pk_mul_f32 v[46:47], v[46:47], v[0:1] op_sel_hi:[1,0]
	v_pk_mul_f32 v[44:45], v[44:45], v[0:1] op_sel_hi:[1,0]
	v_pk_mul_f32 v[42:43], v[42:43], v[0:1] op_sel_hi:[1,0]
	v_pk_mul_f32 v[40:41], v[40:41], v[0:1] op_sel_hi:[1,0]
	v_pk_mul_f32 v[38:39], v[38:39], v[0:1] op_sel_hi:[1,0]
	v_pk_mul_f32 v[36:37], v[36:37], v[0:1] op_sel_hi:[1,0]
	v_pk_mul_f32 v[34:35], v[34:35], v[0:1] op_sel_hi:[1,0]
	v_pk_mul_f32 v[16:17], v[16:17], v[0:1] op_sel_hi:[1,0]
	v_pk_mul_f32 v[14:15], v[14:15], v[0:1] op_sel_hi:[1,0]
	v_pk_mul_f32 v[12:13], v[12:13], v[0:1] op_sel_hi:[1,0]
	v_pk_mul_f32 v[10:11], v[10:11], v[0:1] op_sel_hi:[1,0]
	v_pk_mul_f32 v[8:9], v[8:9], v[0:1] op_sel_hi:[1,0]
	v_pk_mul_f32 v[6:7], v[6:7], v[0:1] op_sel_hi:[1,0]
	v_pk_mul_f32 v[4:5], v[4:5], v[0:1] op_sel_hi:[1,0]
	v_pk_mul_f32 v[2:3], v[2:3], v[0:1] op_sel_hi:[1,0]
	v_pk_mul_f32 v[32:33], v[32:33], v[0:1] op_sel_hi:[1,0]
	v_pk_mul_f32 v[30:31], v[30:31], v[0:1] op_sel_hi:[1,0]
	v_pk_mul_f32 v[28:29], v[28:29], v[0:1] op_sel_hi:[1,0]
	v_pk_mul_f32 v[26:27], v[26:27], v[0:1] op_sel_hi:[1,0]
	v_pk_mul_f32 v[24:25], v[24:25], v[0:1] op_sel_hi:[1,0]
	v_pk_mul_f32 v[22:23], v[22:23], v[0:1] op_sel_hi:[1,0]
	v_pk_mul_f32 v[20:21], v[20:21], v[0:1] op_sel_hi:[1,0]
	v_pk_mul_f32 v[18:19], v[18:19], v[0:1] op_sel_hi:[1,0]
	s_or_b64 s[12:13], s[12:13], s[16:17]
	v_mov_b32_e32 v51, v50
	v_mov_b32_e32 v52, v50
	v_mov_b32_e32 v53, v50
	v_mov_b32_e32 v54, v50
	v_mov_b32_e32 v55, v50
	v_mov_b32_e32 v56, v50
	v_mov_b32_e32 v57, v50
	v_mov_b32_e32 v58, v50
	v_mov_b32_e32 v59, v50
	v_mov_b32_e32 v60, v50
	v_mov_b32_e32 v61, v50
	v_mov_b32_e32 v62, v50
	v_mov_b32_e32 v63, v50
	v_mov_b32_e32 v64, v50
	v_mov_b32_e32 v65, v50
	s_branch .LBB0_1115
.Lbe_win_exit:
	s_waitcnt lgkmcnt(0)
	s_barrier
.LBB0_1128:
	s_nop 2
	ds_read2st64_b32 v[38:39], v222 offset0:209 offset1:210
	ds_read2st64_b32 v[44:45], v222 offset0:205 offset1:206
	ds_read2st64_b32 v[46:47], v222 offset0:207 offset1:208
	ds_read2st64_b32 v[48:49], v222 offset0:211 offset1:212
	ds_read2st64_b32 v[50:51], v222 offset0:213 offset1:214
	ds_read2st64_b32 v[52:53], v222 offset0:215 offset1:216
	ds_read2st64_b32 v[54:55], v222 offset0:217 offset1:218
	s_waitcnt lgkmcnt(6)
	v_mov_b32_e32 v36, v39
	ds_read_b32 v39, v222 offset:56064
	s_waitcnt lgkmcnt(5)
	v_mov_b32_e32 v40, v47
	s_waitcnt lgkmcnt(4)
	v_mov_b32_e32 v37, v48
	v_mov_b32_e32 v41, v38
	v_mov_b32_e32 v42, v45
	v_mov_b32_e32 v43, v46
	s_mov_b64 s[12:13], 0
	v_mov_b32_e32 v35, v44
	v_mov_b32_e32 v44, v49
	s_waitcnt lgkmcnt(3)
	v_mov_b32_e32 v45, v50
	v_mov_b32_e32 v46, v51
	s_waitcnt lgkmcnt(2)
	v_mov_b32_e32 v47, v52
	v_mov_b32_e32 v48, v53
	s_waitcnt lgkmcnt(1)
	v_mov_b32_e32 v49, v54
	v_mov_b32_e32 v38, v55
